# v48 plus: mla_up rms prologue and rope-key copy loads issued in batches instead of one per wait
# speedup vs baseline: 1.0299x; 1.0026x over previous
; DI void mla_up_tile(CParams& p, int mt, int j, int S, char* lds) {
;     ...
;   {
;     const bf16_t* ar = A + (size_t)erow * NPR + half * (K / 2);
;     float ss = 0.f;
;     for (int c = 0; c < K / 16; ++c) {
;       const u32x4 u = *(const u32x4*)(ar + 8 * c);
;       const unsigned uu[4] = {u.x, u.y, u.z, u.w};
; #pragma unroll
;       for (int e = 0; e < 4; ++e) {
;         const float lo = __uint_as_float(uu[e] << 16), hi = __uint_as_float(uu[e] & 0xffff0000u);
;         ss += lo * lo + hi * hi;
;       }
;     }
;     ss += __shfl_xor(ss, 1);
;     if (half == 0) rst[erow] = rsqrtf(ss / (float)K + EPS);
;   }
.LBB0_751:
.Lrms_batch:
	global_load_dwordx4 v[168:171], v[2:3], off
	global_load_dwordx4 v[172:175], v[2:3], off offset:16
	global_load_dwordx4 v[176:179], v[2:3], off offset:32
	global_load_dwordx4 v[180:183], v[2:3], off offset:48
	global_load_dwordx4 v[184:187], v[2:3], off offset:64
	global_load_dwordx4 v[188:191], v[2:3], off offset:80
	global_load_dwordx4 v[192:195], v[2:3], off offset:96
	global_load_dwordx4 v[196:199], v[2:3], off offset:112
	v_lshl_add_u64 v[2:3], v[2:3], 0, 64
	v_lshl_add_u64 v[2:3], v[2:3], 0, 64
	s_add_i32 s8, s8, -8
	s_waitcnt vmcnt(0)
	v_lshlrev_b32_e32 v8, 16, v168
	v_and_b32_e32 v9, 0xffff0000, v168
	v_pk_mul_f32 v[8:9], v[8:9], v[8:9]
	v_and_b32_e32 v11, 0xffff0000, v170
	v_add_f32_e32 v4, v8, v9
	v_and_b32_e32 v10, 0xffff0000, v169
	v_add_f32_e32 v0, v0, v4
	v_lshlrev_b32_e32 v9, 16, v170
	v_lshlrev_b32_e32 v8, 16, v169
	v_pk_mul_f32 v[4:5], v[10:11], v[10:11]
	s_nop 0
	v_pk_fma_f32 v[4:5], v[8:9], v[8:9], v[4:5]
	s_nop 0
	v_add_f32_e32 v0, v4, v0
	v_add_f32_e32 v0, v5, v0
	v_lshlrev_b32_e32 v4, 16, v171
	v_and_b32_e32 v5, 0xffff0000, v171
	v_pk_mul_f32 v[4:5], v[4:5], v[4:5]
	s_nop 0
	v_add_f32_e32 v4, v4, v5
	v_add_f32_e32 v0, v4, v0
	v_lshlrev_b32_e32 v8, 16, v172
	v_and_b32_e32 v9, 0xffff0000, v172
	v_pk_mul_f32 v[8:9], v[8:9], v[8:9]
	v_and_b32_e32 v11, 0xffff0000, v174
	v_add_f32_e32 v4, v8, v9
	v_and_b32_e32 v10, 0xffff0000, v173
	v_add_f32_e32 v0, v0, v4
	v_lshlrev_b32_e32 v9, 16, v174
	v_lshlrev_b32_e32 v8, 16, v173
	v_pk_mul_f32 v[4:5], v[10:11], v[10:11]
	s_nop 0
	v_pk_fma_f32 v[4:5], v[8:9], v[8:9], v[4:5]
	s_nop 0
	v_add_f32_e32 v0, v4, v0
	v_add_f32_e32 v0, v5, v0
	v_lshlrev_b32_e32 v4, 16, v175
	v_and_b32_e32 v5, 0xffff0000, v175
	v_pk_mul_f32 v[4:5], v[4:5], v[4:5]
	s_nop 0
	v_add_f32_e32 v4, v4, v5
	v_add_f32_e32 v0, v4, v0
	v_lshlrev_b32_e32 v8, 16, v176
	v_and_b32_e32 v9, 0xffff0000, v176
	v_pk_mul_f32 v[8:9], v[8:9], v[8:9]
	v_and_b32_e32 v11, 0xffff0000, v178
	v_add_f32_e32 v4, v8, v9
	v_and_b32_e32 v10, 0xffff0000, v177
	v_add_f32_e32 v0, v0, v4
	v_lshlrev_b32_e32 v9, 16, v178
	v_lshlrev_b32_e32 v8, 16, v177
	v_pk_mul_f32 v[4:5], v[10:11], v[10:11]
	s_nop 0
	v_pk_fma_f32 v[4:5], v[8:9], v[8:9], v[4:5]
	s_nop 0
	v_add_f32_e32 v0, v4, v0
	v_add_f32_e32 v0, v5, v0
	v_lshlrev_b32_e32 v4, 16, v179
	v_and_b32_e32 v5, 0xffff0000, v179
	v_pk_mul_f32 v[4:5], v[4:5], v[4:5]
	s_nop 0
	v_add_f32_e32 v4, v4, v5
	v_add_f32_e32 v0, v4, v0
	v_lshlrev_b32_e32 v8, 16, v180
	v_and_b32_e32 v9, 0xffff0000, v180
	v_pk_mul_f32 v[8:9], v[8:9], v[8:9]
	v_and_b32_e32 v11, 0xffff0000, v182
	v_add_f32_e32 v4, v8, v9
	v_and_b32_e32 v10, 0xffff0000, v181
	v_add_f32_e32 v0, v0, v4
	v_lshlrev_b32_e32 v9, 16, v182
	v_lshlrev_b32_e32 v8, 16, v181
	v_pk_mul_f32 v[4:5], v[10:11], v[10:11]
	s_nop 0
	v_pk_fma_f32 v[4:5], v[8:9], v[8:9], v[4:5]
	s_nop 0
	v_add_f32_e32 v0, v4, v0
	v_add_f32_e32 v0, v5, v0
	v_lshlrev_b32_e32 v4, 16, v183
	v_and_b32_e32 v5, 0xffff0000, v183
	v_pk_mul_f32 v[4:5], v[4:5], v[4:5]
	s_nop 0
	v_add_f32_e32 v4, v4, v5
	v_add_f32_e32 v0, v4, v0
	v_lshlrev_b32_e32 v8, 16, v184
	v_and_b32_e32 v9, 0xffff0000, v184
	v_pk_mul_f32 v[8:9], v[8:9], v[8:9]
	v_and_b32_e32 v11, 0xffff0000, v186
	v_add_f32_e32 v4, v8, v9
	v_and_b32_e32 v10, 0xffff0000, v185
	v_add_f32_e32 v0, v0, v4
	v_lshlrev_b32_e32 v9, 16, v186
	v_lshlrev_b32_e32 v8, 16, v185
	v_pk_mul_f32 v[4:5], v[10:11], v[10:11]
	s_nop 0
	v_pk_fma_f32 v[4:5], v[8:9], v[8:9], v[4:5]
	s_nop 0
	v_add_f32_e32 v0, v4, v0
	v_add_f32_e32 v0, v5, v0
	v_lshlrev_b32_e32 v4, 16, v187
	v_and_b32_e32 v5, 0xffff0000, v187
	v_pk_mul_f32 v[4:5], v[4:5], v[4:5]
	s_nop 0
	v_add_f32_e32 v4, v4, v5
	v_add_f32_e32 v0, v4, v0
	v_lshlrev_b32_e32 v8, 16, v188
	v_and_b32_e32 v9, 0xffff0000, v188
	v_pk_mul_f32 v[8:9], v[8:9], v[8:9]
	v_and_b32_e32 v11, 0xffff0000, v190
	v_add_f32_e32 v4, v8, v9
	v_and_b32_e32 v10, 0xffff0000, v189
	v_add_f32_e32 v0, v0, v4
	v_lshlrev_b32_e32 v9, 16, v190
	v_lshlrev_b32_e32 v8, 16, v189
	v_pk_mul_f32 v[4:5], v[10:11], v[10:11]
	s_nop 0
	v_pk_fma_f32 v[4:5], v[8:9], v[8:9], v[4:5]
	s_nop 0
	v_add_f32_e32 v0, v4, v0
	v_add_f32_e32 v0, v5, v0
	v_lshlrev_b32_e32 v4, 16, v191
	v_and_b32_e32 v5, 0xffff0000, v191
	v_pk_mul_f32 v[4:5], v[4:5], v[4:5]
	s_nop 0
	v_add_f32_e32 v4, v4, v5
	v_add_f32_e32 v0, v4, v0
	v_lshlrev_b32_e32 v8, 16, v192
	v_and_b32_e32 v9, 0xffff0000, v192
	v_pk_mul_f32 v[8:9], v[8:9], v[8:9]
	v_and_b32_e32 v11, 0xffff0000, v194
	v_add_f32_e32 v4, v8, v9
	v_and_b32_e32 v10, 0xffff0000, v193
	v_add_f32_e32 v0, v0, v4
	v_lshlrev_b32_e32 v9, 16, v194
	v_lshlrev_b32_e32 v8, 16, v193
	v_pk_mul_f32 v[4:5], v[10:11], v[10:11]
	s_nop 0
	v_pk_fma_f32 v[4:5], v[8:9], v[8:9], v[4:5]
	s_nop 0
	v_add_f32_e32 v0, v4, v0
	v_add_f32_e32 v0, v5, v0
	v_lshlrev_b32_e32 v4, 16, v195
	v_and_b32_e32 v5, 0xffff0000, v195
	v_pk_mul_f32 v[4:5], v[4:5], v[4:5]
	s_nop 0
	v_add_f32_e32 v4, v4, v5
	v_add_f32_e32 v0, v4, v0
	v_lshlrev_b32_e32 v8, 16, v196
	v_and_b32_e32 v9, 0xffff0000, v196
	v_pk_mul_f32 v[8:9], v[8:9], v[8:9]
	v_and_b32_e32 v11, 0xffff0000, v198
	v_add_f32_e32 v4, v8, v9
	v_and_b32_e32 v10, 0xffff0000, v197
	v_add_f32_e32 v0, v0, v4
	v_lshlrev_b32_e32 v9, 16, v198
	v_lshlrev_b32_e32 v8, 16, v197
	v_pk_mul_f32 v[4:5], v[10:11], v[10:11]
	s_nop 0
	v_pk_fma_f32 v[4:5], v[8:9], v[8:9], v[4:5]
	s_nop 0
	v_add_f32_e32 v0, v4, v0
	v_add_f32_e32 v0, v5, v0
	v_lshlrev_b32_e32 v4, 16, v199
	v_and_b32_e32 v5, 0xffff0000, v199
	v_pk_mul_f32 v[4:5], v[4:5], v[4:5]
	s_nop 0
	v_add_f32_e32 v4, v4, v5
	v_add_f32_e32 v0, v4, v0
	s_cmp_eq_u32 s8, 0
	s_cbranch_scc0 .Lrms_batch
	v_and_b32_e32 v3, 64, v225
	v_xor_b32_e32 v2, 1, v225
	v_add_u32_e32 v3, 64, v3
	v_cmp_lt_i32_e32 vcc, v2, v3
	v_cmp_ne_u32_e64 s[46:47], 0, v99
	v_cmp_eq_u32_e64 s[44:45], 0, v99
	v_cndmask_b32_e32 v2, v225, v2, vcc
	v_lshlrev_b32_e32 v2, 2, v2
	ds_bpermute_b32 v2, v2, v0
	v_lshl_add_u32 v105, v101, 2, 16
	s_and_saveexec_b64 s[8:9], s[44:45]
	s_cbranch_execz .LBB0_754
	v_cvt_f32_u32_e32 v3, s82
	s_waitcnt lgkmcnt(0)
	v_add_f32_e32 v0, v0, v2
	v_div_scale_f32 v2, s[60:61], v3, v3, v0
	v_rcp_f32_e32 v4, v2
	v_div_scale_f32 v5, vcc, v0, v3, v0
	v_fma_f32 v6, -v2, v4, 1.0
	v_fmac_f32_e32 v4, v6, v4
	v_mul_f32_e32 v6, v5, v4
	v_fma_f32 v7, -v2, v6, v5
	v_fmac_f32_e32 v6, v7, v4
	v_fma_f32 v2, -v2, v6, v5
	v_div_fmas_f32 v2, v2, v4, v6
	v_div_fixup_f32 v0, v2, v3, v0
	v_add_f32_e32 v0, 0x358637bd, v0
	v_mul_f32_e32 v2, 0x4b800000, v0
	v_cmp_gt_f32_e32 vcc, s15, v0
	s_nop 1
	v_cndmask_b32_e32 v0, v0, v2, vcc
	v_rsq_f32_e32 v0, v0
	s_nop 0
	v_mul_f32_e32 v2, 0x45800000, v0
	v_cndmask_b32_e32 v0, v0, v2, vcc
	v_add_u32_e32 v2, 0x10800, v105
	ds_write_b32 v2, v0

; #define EPI_BEGIN(NI_) _Pragma("unroll") for (int mi = 0; mi < 2; ++mi) _Pragma("unroll") for (int ni = 0; ni < NI_; ++ni) _Pragma("unroll") for (int r = 0; r < 16; ++r) { \
;     const int row = 64 * wm + 32 * mi + crow(r, h2); const int col = 32 * NI_ * wn + 32 * ni + l31;
; DI void mla_up_tile(CParams& p, int mt, int j, int S, char* lds) {
;     ...
;   __syncthreads();
;   EPI_BEGIN(2)
;     Ct[row * 132 + col] = a0[mi][ni][r];
;   EPI_END
;   __syncthreads();
;   const int tok = mt * 128 + erow, pos = tok & (S - 1);
;   const float rs = rst[erow];
;   const float* cr = Ct + erow * 132 + 64 * half;
.LBB0_758:
	v_and_b32_e32 v0, 0xfffffc0, v101
	s_waitcnt vmcnt(5)
	v_lshrrev_b32_e32 v66, 3, v103
	v_and_or_b32 v0, v66, 4, v0
	v_and_b32_e32 v66, 0x5f, v103
	s_movk_i32 s8, 0x210
	v_lshlrev_b32_e32 v66, 2, v66
	v_mul_lo_u32 v0, v0, s8
	v_add3_u32 v0, 16, v66, v0
	s_barrier
	ds_write2_b32 v0, v50, v34 offset1:32
	ds_write2_b32 v0, v51, v35 offset0:132 offset1:164
	v_add_u32_e32 v34, 0x400, v0
	ds_write2_b32 v34, v52, v36 offset0:8 offset1:40
	ds_write2_b32 v34, v53, v37 offset0:140 offset1:172
	v_add_u32_e32 v34, 0x1000, v0
	ds_write2_b32 v34, v54, v38 offset0:32 offset1:64
	ds_write2_b32 v34, v55, v39 offset0:164 offset1:196
	v_add_u32_e32 v34, 0x1400, v0
	ds_write2_b32 v34, v56, v40 offset0:40 offset1:72
	ds_write2_b32 v34, v57, v41 offset0:172 offset1:204
	v_add_u32_e32 v34, 0x2000, v0
	ds_write2_b32 v34, v58, v42 offset0:64 offset1:96
	ds_write2_b32 v34, v59, v43 offset0:196 offset1:228
	v_add_u32_e32 v34, 0x2400, v0
	ds_write2_b32 v34, v60, v44 offset0:72 offset1:104
	ds_write2_b32 v34, v61, v45 offset0:204 offset1:236
	v_add_u32_e32 v34, 0x3000, v0
	ds_write2_b32 v34, v62, v46 offset0:96 offset1:128
	v_add_u32_e32 v34, 0x3200, v0
	ds_write2_b32 v34, v63, v47 offset0:100 offset1:132
	v_add_u32_e32 v34, 0x3400, v0
	ds_write2_b32 v34, v64, v48 offset0:104 offset1:136
	v_add_u32_e32 v34, 0x3600, v0
	ds_write2_b32 v34, v65, v49 offset0:108 offset1:140
	v_add_u32_e32 v34, 0x4000, v0
	ds_write2_b32 v34, v18, v2 offset0:128 offset1:160
	v_add_u32_e32 v2, 0x4400, v0
	ds_write2_b32 v2, v19, v3 offset0:4 offset1:36
	ds_write2_b32 v2, v20, v4 offset0:136 offset1:168
	v_add_u32_e32 v2, 0x4800, v0
	ds_write2_b32 v2, v21, v5 offset0:12 offset1:44
	v_add_u32_e32 v2, 0x5000, v0
	ds_write2_b32 v2, v22, v6 offset0:160 offset1:192
	v_add_u32_e32 v2, 0x5400, v0
	ds_write2_b32 v2, v23, v7 offset0:36 offset1:68
	ds_write2_b32 v2, v24, v8 offset0:168 offset1:200
	v_add_u32_e32 v2, 0x5800, v0
	ds_write2_b32 v2, v25, v9 offset0:44 offset1:76
	v_add_u32_e32 v2, 0x6000, v0
	ds_write2_b32 v2, v26, v10 offset0:192 offset1:224
	v_add_u32_e32 v2, 0x6400, v0
	ds_write2_b32 v2, v27, v11 offset0:68 offset1:100
	ds_write2_b32 v2, v28, v12 offset0:200 offset1:232
	v_add_u32_e32 v2, 0x6800, v0
	ds_write2_b32 v2, v29, v13 offset0:76 offset1:108
	v_add_u32_e32 v2, 0x7200, v0
	ds_write2_b32 v2, v30, v14 offset0:96 offset1:128
	v_add_u32_e32 v2, 0x7400, v0
	ds_write2_b32 v2, v31, v15 offset0:100 offset1:132
	v_add_u32_e32 v2, 0x7600, v0
	v_add_u32_e32 v0, 0x7800, v0
	ds_write2_b32 v0, v33, v17 offset0:108 offset1:140
	v_add_u32_e32 v0, 0x10800, v105
	ds_write2_b32 v2, v32, v16 offset0:104 offset1:136
	s_waitcnt lgkmcnt(0)
	s_barrier
	ds_read_b32 v0, v0
	v_lshl_add_u32 v2, s79, 7, v101
	v_mul_lo_u32 v3, v101, s8
	v_lshlrev_b32_e32 v4, 8, v99
	v_add3_u32 v23, 16, v3, v4
	s_mov_b64 s[8:9], -1
	s_and_b64 vcc, exec, s[6:7]
	v_ashrrev_i32_e32 v3, 31, v2
	s_cbranch_vccz .LBB0_766
; DI void mla_up_tile(CParams& p, int mt, int j, int S, char* lds) {
;     ...
;   } else {
;     bf16_t* dst = half == 0 ? (Kb + ((size_t)tok * 4 + nt) * 96) : (Vb + ((size_t)tok * 4 + nt) * 64);
; #pragma unroll
;     for (int jj = 0; jj < 8; ++jj) {
;       float o[8];
; #pragma unroll
;       for (int e = 0; e < 8; ++e) o[e] = cr[8 * jj + e] * rs;
;       store8bf(dst + 8 * jj, o);
;     }
;     if (half == 0) {
;       const u32x4* src = (const u32x4*)(PR + (size_t)tok * NPR + 4480);
; #pragma unroll
;       for (int jj = 0; jj < 4; ++jj) ((u32x4*)(dst + 64))[jj] = src[jj];
;     }
	s_and_saveexec_b64 s[6:7], s[46:47]
	s_xor_b64 s[6:7], exec, s[6:7]
	v_lshlrev_b64 v[4:5], 9, v[2:3]
	v_lshl_add_u64 v[4:5], s[42:43], 0, v[4:5]
	v_lshl_add_u64 v[4:5], v[4:5], 0, s[60:61]
	s_andn2_saveexec_b64 s[6:7], s[6:7]
	v_lshl_add_u64 v[6:7], v[2:3], 2, s[58:59]
	v_mov_b64_e32 v[4:5], s[50:51]
	v_mad_u64_u32 v[4:5], s[8:9], v6, s81, v[4:5]
	v_mad_i32_i24 v5, v7, s81, v5
	s_or_b64 exec, exec, s[6:7]
	ds_read_b128 v[6:9], v23
	ds_read_b128 v[10:13], v23 offset:16
	ds_read_b128 v[14:17], v23 offset:32
	ds_read_b128 v[18:21], v23 offset:48
	s_waitcnt lgkmcnt(3)
	v_pk_mul_f32 v[6:7], v[0:1], v[6:7] op_sel_hi:[0,1]
	v_pk_mul_f32 v[8:9], v[0:1], v[8:9] op_sel_hi:[0,1]
	s_waitcnt lgkmcnt(2)
	v_pk_mul_f32 v[10:11], v[0:1], v[10:11] op_sel_hi:[0,1]
	v_pk_mul_f32 v[12:13], v[0:1], v[12:13] op_sel_hi:[0,1]
	v_cvt_pk_bf16_f32 v6, v6, v7
	v_cvt_pk_bf16_f32 v7, v8, v9
	v_cvt_pk_bf16_f32 v8, v10, v11
	v_cvt_pk_bf16_f32 v9, v12, v13
	global_store_dwordx4 v[4:5], v[6:9], off
	ds_read_b128 v[10:13], v23 offset:64
	s_waitcnt lgkmcnt(2)
	v_pk_mul_f32 v[6:7], v[0:1], v[14:15] op_sel_hi:[0,1]
	v_pk_mul_f32 v[8:9], v[0:1], v[16:17] op_sel_hi:[0,1]
	s_waitcnt lgkmcnt(1)
	v_pk_mul_f32 v[14:15], v[0:1], v[18:19] op_sel_hi:[0,1]
	v_cvt_pk_bf16_f32 v6, v6, v7
	v_cvt_pk_bf16_f32 v7, v8, v9
	v_cvt_pk_bf16_f32 v8, v14, v15
	ds_read_b128 v[14:17], v23 offset:80
	v_pk_mul_f32 v[18:19], v[0:1], v[20:21] op_sel_hi:[0,1]
	v_cvt_pk_bf16_f32 v9, v18, v19
	global_store_dwordx4 v[4:5], v[6:9], off offset:16
	s_waitcnt lgkmcnt(0)
	v_pk_mul_f32 v[14:15], v[0:1], v[14:15] op_sel_hi:[0,1]
	v_pk_mul_f32 v[6:7], v[0:1], v[10:11] op_sel_hi:[0,1]
	v_pk_mul_f32 v[8:9], v[0:1], v[12:13] op_sel_hi:[0,1]
	v_pk_mul_f32 v[18:19], v[0:1], v[16:17] op_sel_hi:[0,1]
	v_cvt_pk_bf16_f32 v6, v6, v7
	v_cvt_pk_bf16_f32 v7, v8, v9
	ds_read_b128 v[10:13], v23 offset:96
	v_cvt_pk_bf16_f32 v8, v14, v15
	ds_read_b128 v[14:17], v23 offset:112
	v_cvt_pk_bf16_f32 v9, v18, v19
	global_store_dwordx4 v[4:5], v[6:9], off offset:32
	s_waitcnt lgkmcnt(0)
	v_pk_mul_f32 v[14:15], v[0:1], v[14:15] op_sel_hi:[0,1]
	v_pk_mul_f32 v[6:7], v[0:1], v[10:11] op_sel_hi:[0,1]
	v_pk_mul_f32 v[8:9], v[0:1], v[12:13] op_sel_hi:[0,1]
	v_pk_mul_f32 v[18:19], v[0:1], v[16:17] op_sel_hi:[0,1]
	v_cvt_pk_bf16_f32 v6, v6, v7
	v_cvt_pk_bf16_f32 v7, v8, v9
	ds_read_b128 v[10:13], v23 offset:128
	v_cvt_pk_bf16_f32 v8, v14, v15
	ds_read_b128 v[14:17], v23 offset:144
	v_cvt_pk_bf16_f32 v9, v18, v19
	global_store_dwordx4 v[4:5], v[6:9], off offset:48
	s_waitcnt lgkmcnt(0)
	v_pk_mul_f32 v[14:15], v[0:1], v[14:15] op_sel_hi:[0,1]
	v_pk_mul_f32 v[6:7], v[0:1], v[10:11] op_sel_hi:[0,1]
	v_pk_mul_f32 v[8:9], v[0:1], v[12:13] op_sel_hi:[0,1]
	v_pk_mul_f32 v[18:19], v[0:1], v[16:17] op_sel_hi:[0,1]
	v_cvt_pk_bf16_f32 v6, v6, v7
	v_cvt_pk_bf16_f32 v7, v8, v9
	ds_read_b128 v[10:13], v23 offset:160
	v_cvt_pk_bf16_f32 v8, v14, v15
	ds_read_b128 v[14:17], v23 offset:176
	v_cvt_pk_bf16_f32 v9, v18, v19
	global_store_dwordx4 v[4:5], v[6:9], off offset:64
	s_waitcnt lgkmcnt(1)
	s_nop 0
	v_pk_mul_f32 v[6:7], v[0:1], v[10:11] op_sel_hi:[0,1]
	v_pk_mul_f32 v[8:9], v[0:1], v[12:13] op_sel_hi:[0,1]
	s_waitcnt lgkmcnt(0)
	v_pk_mul_f32 v[10:11], v[0:1], v[14:15] op_sel_hi:[0,1]
	v_pk_mul_f32 v[12:13], v[0:1], v[16:17] op_sel_hi:[0,1]
	v_cvt_pk_bf16_f32 v6, v6, v7
	v_cvt_pk_bf16_f32 v7, v8, v9
	v_cvt_pk_bf16_f32 v8, v10, v11
	v_cvt_pk_bf16_f32 v9, v12, v13
	ds_read_b128 v[10:13], v23 offset:192
	global_store_dwordx4 v[4:5], v[6:9], off offset:80
	ds_read_b128 v[6:9], v23 offset:208
	ds_read_b128 v[14:17], v23 offset:224
	ds_read_b128 v[18:21], v23 offset:240
	s_waitcnt lgkmcnt(3)
	v_pk_mul_f32 v[10:11], v[0:1], v[10:11] op_sel_hi:[0,1]
	v_pk_mul_f32 v[12:13], v[0:1], v[12:13] op_sel_hi:[0,1]
	s_waitcnt lgkmcnt(2)
	v_pk_mul_f32 v[24:25], v[0:1], v[6:7] op_sel_hi:[0,1]
	v_pk_mul_f32 v[26:27], v[0:1], v[8:9] op_sel_hi:[0,1]
	v_cvt_pk_bf16_f32 v6, v10, v11
	v_cvt_pk_bf16_f32 v7, v12, v13
	v_cvt_pk_bf16_f32 v8, v24, v25
	v_cvt_pk_bf16_f32 v9, v26, v27
	global_store_dwordx4 v[4:5], v[6:9], off offset:96
	s_waitcnt lgkmcnt(0)
	v_pk_mul_f32 v[10:11], v[0:1], v[18:19] op_sel_hi:[0,1]
	v_pk_mul_f32 v[12:13], v[0:1], v[20:21] op_sel_hi:[0,1]
	v_pk_mul_f32 v[6:7], v[0:1], v[14:15] op_sel_hi:[0,1]
	v_pk_mul_f32 v[8:9], v[0:1], v[16:17] op_sel_hi:[0,1]
	v_cvt_pk_bf16_f32 v6, v6, v7
	v_cvt_pk_bf16_f32 v7, v8, v9
	v_cvt_pk_bf16_f32 v8, v10, v11
	v_cvt_pk_bf16_f32 v9, v12, v13
	global_store_dwordx4 v[4:5], v[6:9], off offset:112
	s_and_saveexec_b64 s[6:7], s[44:45]
	s_xor_b64 s[6:7], exec, s[6:7]
	s_cbranch_execz .LBB0_765
	v_mov_b64_e32 v[6:7], s[34:35]
	v_mad_i64_i32 v[6:7], s[8:9], v2, s16, v[6:7]
	v_add_co_u32_e32 v10, vcc, 0x2000, v6
	s_nop 1
	v_addc_co_u32_e32 v11, vcc, 0, v7, vcc
	global_load_dwordx4 v[168:171], v[10:11], off offset:768
	global_load_dwordx4 v[172:175], v[10:11], off offset:784
	global_load_dwordx4 v[176:179], v[10:11], off offset:800
	global_load_dwordx4 v[180:183], v[10:11], off offset:816
	s_waitcnt vmcnt(0)
	global_store_dwordx4 v[4:5], v[168:171], off offset:128
	global_store_dwordx4 v[4:5], v[172:175], off offset:144
	global_store_dwordx4 v[4:5], v[176:179], off offset:160
	global_store_dwordx4 v[4:5], v[180:183], off offset:176
